# residual-add GEMM epilogues (FFN down projections): each store group waits only for its own load (counted vmcnt) instead of draining all eight loads
# speedup vs baseline: 1.0394x; 1.0078x over previous
;     __device__ __forceinline__ void operator()(const f32x4 (&acc)[2][2][4][2], const pg8::Unit& u, int wr, int wc, int fr, int fq) const {
;         const int row0 = u.pm * 256 + wr * 64 + fr, col0 = u.pn * 256 + wc * 32 + 4 * fq;
; #pragma unroll
;         for (int ai = 0; ai < 2; ++ai)
; #pragma unroll
;             for (int mh = 0; mh < 2; ++mh) {
;                 f32x4 xi[2][2][2];
; #pragma unroll
;                 for (int m = 0; m < 2; ++m)
; #pragma unroll
;                     for (int bj = 0; bj < 2; ++bj)
; #pragma unroll
;                         for (int n = 0; n < 2; ++n) xi[m][bj][n] = *(const f32x4*)(Xin + (size_t)(row0 + ai * 128 + (2 * mh + m) * 16) * D + col0 + bj * 128 + n * 16);
;                 __builtin_amdgcn_sched_barrier(0);
; #pragma unroll
;                 for (int m = 0; m < 2; ++m)
; #pragma unroll
;                     for (int bj = 0; bj < 2; ++bj)
; #pragma unroll
;                         for (int n = 0; n < 2; ++n) *(f32x4*)(Xout + (size_t)(row0 + ai * 128 + (2 * mh + m) * 16) * D + col0 + bj * 128 + n * 16) = xi[m][bj][n] + acc[ai][bj][2 * mh + m][n] * scale;
;                 __builtin_amdgcn_sched_barrier(0);
;             }
;     }
.LBB0_121:
	v_lshl_or_b32 v16, s30, 8, v148
	v_lshl_add_u32 v26, s31, 8, v146
	v_ashrrev_i32_e32 v17, 31, v16
	v_readlane_b32 s2, v254, 52
	v_lshlrev_b64 v[16:17], 2, v[16:17]
	v_readlane_b32 s3, v254, 53
	v_ashrrev_i32_e32 v27, 31, v26
	v_lshlrev_b64 v[24:25], 12, v[26:27]
	v_lshl_add_u64 v[18:19], s[2:3], 0, v[16:17]
	v_lshl_add_u64 v[150:151], v[18:19], 0, v[24:25]
	global_load_dwordx4 v[40:43], v[150:151], off
	global_load_dwordx4 v[168:171], v[150:151], off offset:64
	global_load_dwordx4 v[172:175], v[150:151], off offset:512
	global_load_dwordx4 v[176:179], v[150:151], off offset:576
	v_or_b32_e32 v150, 16, v26
	v_ashrrev_i32_e32 v151, 31, v150
	v_lshlrev_b64 v[150:151], 12, v[150:151]
	v_lshl_add_u64 v[158:159], v[18:19], 0, v[150:151]
	global_load_dwordx4 v[180:183], v[158:159], off
	global_load_dwordx4 v[184:187], v[158:159], off offset:64
	global_load_dwordx4 v[188:191], v[158:159], off offset:512
	global_load_dwordx4 v[192:195], v[158:159], off offset:576
	s_waitcnt vmcnt(7)
	v_pk_add_f32 v[42:43], v[134:135], v[42:43]
	v_lshl_add_u64 v[134:135], s[2:3], 0, v[24:25]
	v_pk_add_f32 v[40:41], v[136:137], v[40:41]
	v_lshl_add_u64 v[134:135], v[134:135], 0, v[16:17]
	global_store_dwordx4 v[134:135], v[40:43], off
	s_waitcnt vmcnt(7)
	s_nop 1
	v_pk_add_f32 v[42:43], v[126:127], v[170:171]
	v_pk_add_f32 v[40:41], v[124:125], v[168:169]
	global_store_dwordx4 v[134:135], v[40:43], off offset:64
	s_waitcnt vmcnt(7)
	s_nop 1
	v_pk_add_f32 v[42:43], v[144:145], v[174:175]
	v_pk_add_f32 v[40:41], v[142:143], v[172:173]
	global_store_dwordx4 v[134:135], v[40:43], off offset:512
	s_waitcnt vmcnt(7)
	s_nop 1
	v_pk_add_f32 v[42:43], v[140:141], v[178:179]
	v_pk_add_f32 v[40:41], v[138:139], v[176:177]
	global_store_dwordx4 v[134:135], v[40:43], off offset:576
	s_waitcnt vmcnt(7)
	s_nop 1
	v_pk_add_f32 v[40:41], v[116:117], v[180:181]
	v_lshl_add_u64 v[116:117], s[2:3], 0, v[150:151]
	v_pk_add_f32 v[42:43], v[118:119], v[182:183]
	v_lshl_add_u64 v[116:117], v[116:117], 0, v[16:17]
	global_store_dwordx4 v[116:117], v[40:43], off
	s_waitcnt vmcnt(7)
	s_nop 1
	v_pk_add_f32 v[42:43], v[110:111], v[186:187]
	v_pk_add_f32 v[40:41], v[108:109], v[184:185]
	global_store_dwordx4 v[116:117], v[40:43], off offset:64
	s_waitcnt vmcnt(7)
	s_nop 1
	v_pk_add_f32 v[42:43], v[122:123], v[190:191]
	v_pk_add_f32 v[40:41], v[120:121], v[188:189]
	global_store_dwordx4 v[116:117], v[40:43], off offset:512
	s_waitcnt vmcnt(7)
	s_nop 1
	v_pk_add_f32 v[42:43], v[114:115], v[194:195]
	v_pk_add_f32 v[40:41], v[112:113], v[192:193]
	global_store_dwordx4 v[116:117], v[40:43], off offset:576
	s_nop 1
	v_or_b32_e32 v40, 32, v26
	v_or_b32_e32 v26, 48, v26
	v_ashrrev_i32_e32 v41, 31, v40
	v_ashrrev_i32_e32 v27, 31, v26
	v_lshlrev_b64 v[142:143], 12, v[40:41]
	v_lshlrev_b64 v[26:27], 12, v[26:27]
	v_lshl_add_u64 v[116:117], v[18:19], 0, v[142:143]
	v_lshl_add_u64 v[138:139], v[18:19], 0, v[26:27]
	global_load_dwordx4 v[40:43], v[116:117], off
	global_load_dwordx4 v[108:111], v[116:117], off offset:64
	global_load_dwordx4 v[112:115], v[116:117], off offset:512
	s_nop 0
	global_load_dwordx4 v[116:119], v[116:117], off offset:576
	s_nop 0
	global_load_dwordx4 v[120:123], v[138:139], off
	global_load_dwordx4 v[124:127], v[138:139], off offset:64
	global_load_dwordx4 v[134:137], v[138:139], off offset:512
	s_nop 0
	global_load_dwordx4 v[138:141], v[138:139], off offset:576
	s_waitcnt vmcnt(7)
	v_pk_add_f32 v[40:41], v[100:101], v[40:41]
	v_lshl_add_u64 v[100:101], s[2:3], 0, v[142:143]
	v_pk_add_f32 v[42:43], v[102:103], v[42:43]
	v_lshl_add_u64 v[100:101], v[100:101], 0, v[16:17]
	global_store_dwordx4 v[100:101], v[40:43], off
	s_waitcnt vmcnt(7)
	v_lshl_add_u64 v[26:27], s[2:3], 0, v[26:27]
	v_lshl_add_u64 v[26:27], v[26:27], 0, v[16:17]
	v_pk_add_f32 v[42:43], v[94:95], v[110:111]
	v_pk_add_f32 v[40:41], v[92:93], v[108:109]
	global_store_dwordx4 v[100:101], v[40:43], off offset:64
	s_waitcnt vmcnt(7)
	s_nop 1
	v_pk_add_f32 v[42:43], v[106:107], v[114:115]
	v_pk_add_f32 v[40:41], v[104:105], v[112:113]
	global_store_dwordx4 v[100:101], v[40:43], off offset:512
	s_waitcnt vmcnt(7)
	s_nop 1
	v_pk_add_f32 v[42:43], v[98:99], v[118:119]
	v_pk_add_f32 v[40:41], v[96:97], v[116:117]
	global_store_dwordx4 v[100:101], v[40:43], off offset:576
	s_waitcnt vmcnt(7)
	s_nop 1
	v_pk_add_f32 v[42:43], v[86:87], v[122:123]
	v_pk_add_f32 v[40:41], v[84:85], v[120:121]
	global_store_dwordx4 v[26:27], v[40:43], off
	s_waitcnt vmcnt(7)
	s_nop 1
	v_pk_add_f32 v[42:43], v[74:75], v[126:127]
	v_pk_add_f32 v[40:41], v[72:73], v[124:125]
	global_store_dwordx4 v[26:27], v[40:43], off offset:64
	s_waitcnt vmcnt(7)
;     __device__ __forceinline__ void operator()(const f32x4 (&acc)[2][2][4][2], const pg8::Unit& u, int wr, int wc, int fr, int fq) const {
;         const int row0 = u.pm * 256 + wr * 64 + fr, col0 = u.pn * 256 + wc * 32 + 4 * fq;
; #pragma unroll
;         for (int ai = 0; ai < 2; ++ai)
; #pragma unroll
;             for (int mh = 0; mh < 2; ++mh) {
;                 f32x4 xi[2][2][2];
; #pragma unroll
;                 for (int m = 0; m < 2; ++m)
; #pragma unroll
;                     for (int bj = 0; bj < 2; ++bj)
; #pragma unroll
;                         for (int n = 0; n < 2; ++n) xi[m][bj][n] = *(const f32x4*)(Xin + (size_t)(row0 + ai * 128 + (2 * mh + m) * 16) * D + col0 + bj * 128 + n * 16);
;                 __builtin_amdgcn_sched_barrier(0);
; #pragma unroll
;                 for (int m = 0; m < 2; ++m)
; #pragma unroll
;                     for (int bj = 0; bj < 2; ++bj)
; #pragma unroll
;                         for (int n = 0; n < 2; ++n) *(f32x4*)(Xout + (size_t)(row0 + ai * 128 + (2 * mh + m) * 16) * D + col0 + bj * 128 + n * 16) = xi[m][bj][n] + acc[ai][bj][2 * mh + m][n] * scale;
;                 __builtin_amdgcn_sched_barrier(0);
;             }
;     }
	s_nop 1
	v_pk_add_f32 v[42:43], v[90:91], v[136:137]
	v_pk_add_f32 v[40:41], v[88:89], v[134:135]
	global_store_dwordx4 v[26:27], v[40:43], off offset:512
	s_waitcnt vmcnt(7)
	s_nop 1
	v_pk_add_f32 v[42:43], v[82:83], v[140:141]
	v_pk_add_f32 v[40:41], v[80:81], v[138:139]
	global_store_dwordx4 v[26:27], v[40:43], off offset:576
	s_mov_b64 s[0:1], 0x80000
	v_lshl_add_u64 v[26:27], v[24:25], 0, s[0:1]
	s_mov_b64 s[0:1], 0x90000
	v_lshl_add_u64 v[104:105], v[24:25], 0, s[0:1]
	v_lshl_add_u64 v[84:85], v[18:19], 0, v[26:27]
	v_lshl_add_u64 v[100:101], v[18:19], 0, v[104:105]
	global_load_dwordx4 v[40:43], v[84:85], off
	global_load_dwordx4 v[72:75], v[84:85], off offset:64
	global_load_dwordx4 v[80:83], v[84:85], off offset:512
	s_nop 0
	global_load_dwordx4 v[84:87], v[84:85], off offset:576
	s_nop 0
	global_load_dwordx4 v[88:91], v[100:101], off
	global_load_dwordx4 v[92:95], v[100:101], off offset:64
	global_load_dwordx4 v[96:99], v[100:101], off offset:512
	s_nop 0
	global_load_dwordx4 v[100:103], v[100:101], off offset:576
	v_lshl_add_u64 v[26:27], s[2:3], 0, v[26:27]
	s_waitcnt vmcnt(7)
	v_pk_add_f32 v[42:43], v[66:67], v[42:43]
	v_pk_add_f32 v[40:41], v[64:65], v[40:41]
	v_lshl_add_u64 v[26:27], v[26:27], 0, v[16:17]
	global_store_dwordx4 v[26:27], v[40:43], off
	s_waitcnt vmcnt(7)
	s_nop 1
	v_pk_add_f32 v[42:43], v[62:63], v[74:75]
	v_pk_add_f32 v[40:41], v[60:61], v[72:73]
	global_store_dwordx4 v[26:27], v[40:43], off offset:64
	s_waitcnt vmcnt(7)
	s_nop 1
	v_pk_add_f32 v[42:43], v[78:79], v[82:83]
	v_pk_add_f32 v[40:41], v[76:77], v[80:81]
	global_store_dwordx4 v[26:27], v[40:43], off offset:512
	s_waitcnt vmcnt(7)
	s_nop 1
	v_pk_add_f32 v[42:43], v[70:71], v[86:87]
	v_pk_add_f32 v[40:41], v[68:69], v[84:85]
	global_store_dwordx4 v[26:27], v[40:43], off offset:576
	s_waitcnt vmcnt(7)
	v_lshl_add_u64 v[26:27], s[2:3], 0, v[104:105]
	v_lshl_add_u64 v[26:27], v[26:27], 0, v[16:17]
	v_pk_add_f32 v[42:43], v[54:55], v[90:91]
	v_pk_add_f32 v[40:41], v[52:53], v[88:89]
	global_store_dwordx4 v[26:27], v[40:43], off
	s_waitcnt vmcnt(7)
	s_nop 1
	v_pk_add_f32 v[42:43], v[46:47], v[94:95]
	v_pk_add_f32 v[40:41], v[44:45], v[92:93]
	global_store_dwordx4 v[26:27], v[40:43], off offset:64
	s_waitcnt vmcnt(7)
	s_nop 1
	v_pk_add_f32 v[42:43], v[58:59], v[98:99]
	v_pk_add_f32 v[40:41], v[56:57], v[96:97]
	global_store_dwordx4 v[26:27], v[40:43], off offset:512
	s_waitcnt vmcnt(7)
	s_nop 1
	v_pk_add_f32 v[42:43], v[50:51], v[102:103]
	v_pk_add_f32 v[40:41], v[48:49], v[100:101]
	global_store_dwordx4 v[26:27], v[40:43], off offset:576
	s_mov_b64 s[0:1], 0xa0000
	v_lshl_add_u64 v[68:69], v[24:25], 0, s[0:1]
	s_mov_b64 s[0:1], 0xb0000
	v_lshl_add_u64 v[70:71], v[24:25], 0, s[0:1]
	v_lshl_add_u64 v[26:27], v[18:19], 0, v[68:69]
	v_lshl_add_u64 v[18:19], v[18:19], 0, v[70:71]
	global_load_dwordx4 v[40:43], v[26:27], off
	global_load_dwordx4 v[44:47], v[26:27], off offset:64
	global_load_dwordx4 v[48:51], v[26:27], off offset:512
	global_load_dwordx4 v[52:55], v[26:27], off offset:576
	s_nop 0
	global_load_dwordx4 v[24:27], v[18:19], off
	global_load_dwordx4 v[56:59], v[18:19], off offset:64
	global_load_dwordx4 v[60:63], v[18:19], off offset:512
	global_load_dwordx4 v[64:67], v[18:19], off offset:576
	v_lshl_add_u64 v[18:19], s[2:3], 0, v[68:69]
	s_waitcnt vmcnt(0)
	v_pk_add_f32 v[28:29], v[28:29], v[40:41]
	v_lshl_add_u64 v[40:41], v[18:19], 0, v[16:17]
	v_pk_add_f32 v[22:23], v[22:23], v[46:47]
	v_pk_add_f32 v[20:21], v[20:21], v[44:45]
	global_store_dwordx4 v[40:41], v[20:23], off offset:64
	v_pk_add_f32 v[18:19], v[36:37], v[48:49]
	v_pk_add_f32 v[30:31], v[30:31], v[42:43]
	v_pk_add_f32 v[20:21], v[38:39], v[50:51]
	global_store_dwordx4 v[40:41], v[18:21], off offset:512
	v_pk_add_f32 v[14:15], v[14:15], v[26:27]
	v_pk_add_f32 v[12:13], v[12:13], v[24:25]
	v_pk_add_f32 v[20:21], v[34:35], v[54:55]
	v_pk_add_f32 v[18:19], v[32:33], v[52:53]
	global_store_dwordx4 v[40:41], v[18:21], off offset:576
	v_pk_add_f32 v[10:11], v[10:11], v[58:59]
	v_pk_add_f32 v[8:9], v[8:9], v[56:57]
	v_lshl_add_u64 v[18:19], s[2:3], 0, v[70:71]
	v_lshl_add_u64 v[16:17], v[18:19], 0, v[16:17]
	v_pk_add_f32 v[6:7], v[6:7], v[62:63]
	v_pk_add_f32 v[4:5], v[4:5], v[60:61]
	v_pk_add_f32 v[2:3], v[2:3], v[66:67]
	v_pk_add_f32 v[0:1], v[0:1], v[64:65]
	global_store_dwordx4 v[40:41], v[28:31], off
	global_store_dwordx4 v[16:17], v[12:15], off
	global_store_dwordx4 v[16:17], v[8:11], off offset:64
	global_store_dwordx4 v[16:17], v[4:7], off offset:512
	global_store_dwordx4 v[16:17], v[0:3], off offset:576
	s_and_b64 vcc, exec, s[4:5]
	s_mov_b64 s[0:1], -1
	s_cbranch_vccnz .LBB0_104
	s_andn2_b64 vcc, exec, s[16:17]
	s_cbranch_vccnz .LBB0_103
	s_barrier
	s_branch .LBB0_103

;     __device__ __forceinline__ void operator()(const f32x4 (&acc)[2][2][4][2], const pg8::Unit& u, int wr, int wc, int fr, int fq) const {
;     ...
;         for (int ai = 0; ai < 2; ++ai)
; #pragma unroll
;             for (int mh = 0; mh < 2; ++mh) {
;                 f32x4 xi[2][2][2];
; #pragma unroll
;                 for (int m = 0; m < 2; ++m)
; #pragma unroll
;                     for (int bj = 0; bj < 2; ++bj)
; #pragma unroll
;                         for (int n = 0; n < 2; ++n) xi[m][bj][n] = *(const f32x4*)(Xin + (size_t)(row0 + ai * 128 + (2 * mh + m) * 16) * D + col0 + bj * 128 + n * 16);
;                 __builtin_amdgcn_sched_barrier(0);
; #pragma unroll
;                 for (int m = 0; m < 2; ++m)
; #pragma unroll
;                     for (int bj = 0; bj < 2; ++bj)
; #pragma unroll
;                         for (int n = 0; n < 2; ++n) *(f32x4*)(Xout + (size_t)(row0 + ai * 128 + (2 * mh + m) * 16) * D + col0 + bj * 128 + n * 16) = xi[m][bj][n] + acc[ai][bj][2 * mh + m][n] * scale;
.LBB0_817:
	v_lshl_or_b32 v16, s34, 8, v148
	v_lshl_add_u32 v26, s35, 8, v146
	v_ashrrev_i32_e32 v17, 31, v16
	v_lshlrev_b64 v[16:17], 2, v[16:17]
	v_ashrrev_i32_e32 v27, 31, v26
	v_lshl_add_u64 v[18:19], s[12:13], 0, v[16:17]
	v_lshlrev_b64 v[24:25], 12, v[26:27]
	v_lshl_add_u64 v[150:151], v[18:19], 0, v[24:25]
	global_load_dwordx4 v[40:43], v[150:151], off
	global_load_dwordx4 v[168:171], v[150:151], off offset:64
	global_load_dwordx4 v[172:175], v[150:151], off offset:512
	global_load_dwordx4 v[176:179], v[150:151], off offset:576
	v_or_b32_e32 v150, 16, v26
	v_ashrrev_i32_e32 v151, 31, v150
	v_lshlrev_b64 v[150:151], 12, v[150:151]
	v_lshl_add_u64 v[158:159], v[18:19], 0, v[150:151]
	global_load_dwordx4 v[180:183], v[158:159], off
	global_load_dwordx4 v[184:187], v[158:159], off offset:64
	global_load_dwordx4 v[188:191], v[158:159], off offset:512
	global_load_dwordx4 v[192:195], v[158:159], off offset:576
	v_readlane_b32 s2, v254, 52
	v_readlane_b32 s3, v254, 53
	s_waitcnt vmcnt(7)
	v_pk_add_f32 v[42:43], v[134:135], v[42:43]
	v_pk_add_f32 v[40:41], v[136:137], v[40:41]
	v_lshl_add_u64 v[134:135], s[2:3], 0, v[24:25]
	v_lshl_add_u64 v[134:135], v[134:135], 0, v[16:17]
	global_store_dwordx4 v[134:135], v[40:43], off
	s_waitcnt vmcnt(7)
	s_nop 1
	v_pk_add_f32 v[42:43], v[126:127], v[170:171]
	v_pk_add_f32 v[40:41], v[124:125], v[168:169]
	global_store_dwordx4 v[134:135], v[40:43], off offset:64
	s_waitcnt vmcnt(7)
	s_nop 1
	v_pk_add_f32 v[42:43], v[144:145], v[174:175]
	v_pk_add_f32 v[40:41], v[142:143], v[172:173]
	global_store_dwordx4 v[134:135], v[40:43], off offset:512
	s_waitcnt vmcnt(7)
	s_nop 1
	v_pk_add_f32 v[42:43], v[140:141], v[178:179]
	v_pk_add_f32 v[40:41], v[138:139], v[176:177]
	global_store_dwordx4 v[134:135], v[40:43], off offset:576
	s_waitcnt vmcnt(7)
	s_nop 1
	v_pk_add_f32 v[40:41], v[116:117], v[180:181]
	v_lshl_add_u64 v[116:117], s[2:3], 0, v[150:151]
	v_pk_add_f32 v[42:43], v[118:119], v[182:183]
	v_lshl_add_u64 v[116:117], v[116:117], 0, v[16:17]
	global_store_dwordx4 v[116:117], v[40:43], off
	s_waitcnt vmcnt(7)
	s_nop 1
	v_pk_add_f32 v[42:43], v[110:111], v[186:187]
	v_pk_add_f32 v[40:41], v[108:109], v[184:185]
	global_store_dwordx4 v[116:117], v[40:43], off offset:64
	s_waitcnt vmcnt(7)
	s_nop 1
	v_pk_add_f32 v[42:43], v[122:123], v[190:191]
	v_pk_add_f32 v[40:41], v[120:121], v[188:189]
	global_store_dwordx4 v[116:117], v[40:43], off offset:512
	s_waitcnt vmcnt(7)
	s_nop 1
	v_pk_add_f32 v[42:43], v[114:115], v[194:195]
	v_pk_add_f32 v[40:41], v[112:113], v[192:193]
	global_store_dwordx4 v[116:117], v[40:43], off offset:576
	s_nop 1
	v_or_b32_e32 v40, 32, v26
	v_or_b32_e32 v26, 48, v26
	v_ashrrev_i32_e32 v41, 31, v40
	v_ashrrev_i32_e32 v27, 31, v26
	v_lshlrev_b64 v[142:143], 12, v[40:41]
	v_lshlrev_b64 v[26:27], 12, v[26:27]
	v_lshl_add_u64 v[116:117], v[18:19], 0, v[142:143]
	v_lshl_add_u64 v[138:139], v[18:19], 0, v[26:27]
	global_load_dwordx4 v[40:43], v[116:117], off
	global_load_dwordx4 v[108:111], v[116:117], off offset:64
	global_load_dwordx4 v[112:115], v[116:117], off offset:512
	s_nop 0
	global_load_dwordx4 v[116:119], v[116:117], off offset:576
	s_nop 0
	global_load_dwordx4 v[120:123], v[138:139], off
	global_load_dwordx4 v[124:127], v[138:139], off offset:64
	global_load_dwordx4 v[134:137], v[138:139], off offset:512
	s_nop 0
	global_load_dwordx4 v[138:141], v[138:139], off offset:576
	s_waitcnt vmcnt(7)
	v_pk_add_f32 v[40:41], v[100:101], v[40:41]
	v_lshl_add_u64 v[100:101], s[2:3], 0, v[142:143]
	v_pk_add_f32 v[42:43], v[102:103], v[42:43]
	v_lshl_add_u64 v[100:101], v[100:101], 0, v[16:17]
	global_store_dwordx4 v[100:101], v[40:43], off
	s_waitcnt vmcnt(7)
	v_lshl_add_u64 v[26:27], s[2:3], 0, v[26:27]
	v_lshl_add_u64 v[26:27], v[26:27], 0, v[16:17]
	v_pk_add_f32 v[42:43], v[94:95], v[110:111]
	v_pk_add_f32 v[40:41], v[92:93], v[108:109]
	global_store_dwordx4 v[100:101], v[40:43], off offset:64
	s_waitcnt vmcnt(7)
	s_nop 1
	v_pk_add_f32 v[42:43], v[106:107], v[114:115]
	v_pk_add_f32 v[40:41], v[104:105], v[112:113]
	global_store_dwordx4 v[100:101], v[40:43], off offset:512
	s_waitcnt vmcnt(7)
	s_nop 1
	v_pk_add_f32 v[42:43], v[98:99], v[118:119]
	v_pk_add_f32 v[40:41], v[96:97], v[116:117]
	global_store_dwordx4 v[100:101], v[40:43], off offset:576
	s_waitcnt vmcnt(7)
	s_nop 1
	v_pk_add_f32 v[42:43], v[86:87], v[122:123]
	v_pk_add_f32 v[40:41], v[84:85], v[120:121]
	global_store_dwordx4 v[26:27], v[40:43], off
	s_waitcnt vmcnt(7)
	s_nop 1
	v_pk_add_f32 v[42:43], v[74:75], v[126:127]
	v_pk_add_f32 v[40:41], v[72:73], v[124:125]
	global_store_dwordx4 v[26:27], v[40:43], off offset:64
	s_waitcnt vmcnt(7)
; #define PG8_BAR __builtin_amdgcn_s_barrier()
; template <class Epi, class Sched, bool ALIGN_EPI = false, bool SP2 = false>
; __device__ __forceinline__ void gemm_phase(PG8_LAS unsigned char* lds, const Gemm g, const Sched& S, const Epi& E) {
;     ...
;         if constexpr (ALIGN_EPI) { if (wr == 0) PG8_BAR; }
;         if constexpr (!Epi::AFTER_DRAIN) { E(acc, cur, wr, wc, fr, fq); S.done(cur); }
;         if (!has_next) break;
; #pragma unroll
;         for (int a = 0; a < 2; ++a)
; #pragma unroll
;             for (int b = 0; b < 2; ++b)
; #pragma unroll
;                 for (int m = 0; m < 4; ++m)
; #pragma unroll
;                     for (int n = 0; n < 2; ++n) acc[a][b][m][n] = (f32x4){0.f, 0.f, 0.f, 0.f};
;         cur = nxt; cA = nA; cB = nB; ++ui;
;         if constexpr (ALIGN_EPI) { if (wr == 1) PG8_BAR; }
;     __device__ __forceinline__ void operator()(const f32x4 (&acc)[2][2][4][2], const pg8::Unit& u, int wr, int wc, int fr, int fq) const {
;     ...
;         for (int ai = 0; ai < 2; ++ai)
; #pragma unroll
;             for (int mh = 0; mh < 2; ++mh) {
;                 f32x4 xi[2][2][2];
; #pragma unroll
;                 for (int m = 0; m < 2; ++m)
; #pragma unroll
;                     for (int bj = 0; bj < 2; ++bj)
; #pragma unroll
;                         for (int n = 0; n < 2; ++n) xi[m][bj][n] = *(const f32x4*)(Xin + (size_t)(row0 + ai * 128 + (2 * mh + m) * 16) * D + col0 + bj * 128 + n * 16);
;                 __builtin_amdgcn_sched_barrier(0);
; #pragma unroll
;                 for (int m = 0; m < 2; ++m)
; #pragma unroll
;                     for (int bj = 0; bj < 2; ++bj)
; #pragma unroll
;                         for (int n = 0; n < 2; ++n) *(f32x4*)(Xout + (size_t)(row0 + ai * 128 + (2 * mh + m) * 16) * D + col0 + bj * 128 + n * 16) = xi[m][bj][n] + acc[ai][bj][2 * mh + m][n] * scale;
;                 __builtin_amdgcn_sched_barrier(0);
;             }
	s_nop 1
	v_pk_add_f32 v[42:43], v[90:91], v[136:137]
	v_pk_add_f32 v[40:41], v[88:89], v[134:135]
	global_store_dwordx4 v[26:27], v[40:43], off offset:512
	s_waitcnt vmcnt(7)
	s_nop 1
	v_pk_add_f32 v[42:43], v[82:83], v[140:141]
	v_pk_add_f32 v[40:41], v[80:81], v[138:139]
	global_store_dwordx4 v[26:27], v[40:43], off offset:576
	s_mov_b64 s[0:1], 0x80000
	v_lshl_add_u64 v[26:27], v[24:25], 0, s[0:1]
	s_mov_b64 s[0:1], 0x90000
	v_lshl_add_u64 v[104:105], v[24:25], 0, s[0:1]
	v_lshl_add_u64 v[84:85], v[18:19], 0, v[26:27]
	v_lshl_add_u64 v[100:101], v[18:19], 0, v[104:105]
	global_load_dwordx4 v[40:43], v[84:85], off
	global_load_dwordx4 v[72:75], v[84:85], off offset:64
	global_load_dwordx4 v[80:83], v[84:85], off offset:512
	s_nop 0
	global_load_dwordx4 v[84:87], v[84:85], off offset:576
	s_nop 0
	global_load_dwordx4 v[88:91], v[100:101], off
	global_load_dwordx4 v[92:95], v[100:101], off offset:64
	global_load_dwordx4 v[96:99], v[100:101], off offset:512
	s_nop 0
	global_load_dwordx4 v[100:103], v[100:101], off offset:576
	v_lshl_add_u64 v[26:27], s[2:3], 0, v[26:27]
	s_waitcnt vmcnt(7)
	v_pk_add_f32 v[42:43], v[66:67], v[42:43]
	v_pk_add_f32 v[40:41], v[64:65], v[40:41]
	v_lshl_add_u64 v[26:27], v[26:27], 0, v[16:17]
	global_store_dwordx4 v[26:27], v[40:43], off
	s_waitcnt vmcnt(7)
	s_nop 1
	v_pk_add_f32 v[42:43], v[62:63], v[74:75]
	v_pk_add_f32 v[40:41], v[60:61], v[72:73]
	global_store_dwordx4 v[26:27], v[40:43], off offset:64
	s_waitcnt vmcnt(7)
	s_nop 1
	v_pk_add_f32 v[42:43], v[78:79], v[82:83]
	v_pk_add_f32 v[40:41], v[76:77], v[80:81]
	global_store_dwordx4 v[26:27], v[40:43], off offset:512
	s_waitcnt vmcnt(7)
	s_nop 1
	v_pk_add_f32 v[42:43], v[70:71], v[86:87]
	v_pk_add_f32 v[40:41], v[68:69], v[84:85]
	global_store_dwordx4 v[26:27], v[40:43], off offset:576
	s_waitcnt vmcnt(7)
	v_lshl_add_u64 v[26:27], s[2:3], 0, v[104:105]
	v_lshl_add_u64 v[26:27], v[26:27], 0, v[16:17]
	v_pk_add_f32 v[42:43], v[54:55], v[90:91]
	v_pk_add_f32 v[40:41], v[52:53], v[88:89]
	global_store_dwordx4 v[26:27], v[40:43], off
	s_waitcnt vmcnt(7)
	s_nop 1
	v_pk_add_f32 v[42:43], v[46:47], v[94:95]
	v_pk_add_f32 v[40:41], v[44:45], v[92:93]
	global_store_dwordx4 v[26:27], v[40:43], off offset:64
	s_waitcnt vmcnt(7)
	s_nop 1
	v_pk_add_f32 v[42:43], v[58:59], v[98:99]
	v_pk_add_f32 v[40:41], v[56:57], v[96:97]
	global_store_dwordx4 v[26:27], v[40:43], off offset:512
	s_waitcnt vmcnt(7)
	s_nop 1
	v_pk_add_f32 v[42:43], v[50:51], v[102:103]
	v_pk_add_f32 v[40:41], v[48:49], v[100:101]
	global_store_dwordx4 v[26:27], v[40:43], off offset:576
	s_mov_b64 s[0:1], 0xa0000
	v_lshl_add_u64 v[68:69], v[24:25], 0, s[0:1]
	s_mov_b64 s[0:1], 0xb0000
	v_lshl_add_u64 v[70:71], v[24:25], 0, s[0:1]
	v_lshl_add_u64 v[26:27], v[18:19], 0, v[68:69]
	v_lshl_add_u64 v[18:19], v[18:19], 0, v[70:71]
	global_load_dwordx4 v[40:43], v[26:27], off
	global_load_dwordx4 v[44:47], v[26:27], off offset:64
	global_load_dwordx4 v[48:51], v[26:27], off offset:512
	global_load_dwordx4 v[52:55], v[26:27], off offset:576
	s_nop 0
	global_load_dwordx4 v[24:27], v[18:19], off
	global_load_dwordx4 v[56:59], v[18:19], off offset:64
	global_load_dwordx4 v[60:63], v[18:19], off offset:512
	global_load_dwordx4 v[64:67], v[18:19], off offset:576
	v_lshl_add_u64 v[18:19], s[2:3], 0, v[68:69]
	s_waitcnt vmcnt(0)
	v_pk_add_f32 v[28:29], v[28:29], v[40:41]
	v_lshl_add_u64 v[40:41], v[18:19], 0, v[16:17]
	v_pk_add_f32 v[22:23], v[22:23], v[46:47]
	v_pk_add_f32 v[20:21], v[20:21], v[44:45]
	global_store_dwordx4 v[40:41], v[20:23], off offset:64
	v_pk_add_f32 v[18:19], v[36:37], v[48:49]
	v_pk_add_f32 v[30:31], v[30:31], v[42:43]
	v_pk_add_f32 v[20:21], v[38:39], v[50:51]
	global_store_dwordx4 v[40:41], v[18:21], off offset:512
	v_pk_add_f32 v[14:15], v[14:15], v[26:27]
	v_pk_add_f32 v[12:13], v[12:13], v[24:25]
	v_pk_add_f32 v[20:21], v[34:35], v[54:55]
	v_pk_add_f32 v[18:19], v[32:33], v[52:53]
	global_store_dwordx4 v[40:41], v[18:21], off offset:576
	v_pk_add_f32 v[10:11], v[10:11], v[58:59]
	v_pk_add_f32 v[8:9], v[8:9], v[56:57]
	v_lshl_add_u64 v[18:19], s[2:3], 0, v[70:71]
	v_lshl_add_u64 v[16:17], v[18:19], 0, v[16:17]
	v_pk_add_f32 v[6:7], v[6:7], v[62:63]
	v_pk_add_f32 v[4:5], v[4:5], v[60:61]
	v_pk_add_f32 v[2:3], v[2:3], v[66:67]
	v_pk_add_f32 v[0:1], v[0:1], v[64:65]
	global_store_dwordx4 v[40:41], v[28:31], off
	global_store_dwordx4 v[16:17], v[12:15], off
	global_store_dwordx4 v[16:17], v[8:11], off offset:64
	global_store_dwordx4 v[16:17], v[4:7], off offset:512
	global_store_dwordx4 v[16:17], v[0:3], off offset:576
	s_and_b64 vcc, exec, s[4:5]
	s_mov_b64 s[0:1], -1
	s_cbranch_vccnz .LBB0_800
	s_andn2_b64 vcc, exec, s[16:17]
	s_cbranch_vccnz .LBB0_799
	s_barrier
	s_branch .LBB0_799
